# counted vmcnt(15) ladder in out-proj and MLP-down residual epilogues (compute starts at first load return), on combined v52
# speedup vs baseline: 1.0097x; 1.0008x over previous
; __device__ __forceinline__ u32x4 pack8(const f32x4 v0, const f32x4 v1) { u32x4 w; w.x = cvt_pk_bf16(v0[0], v0[1]); w.y = cvt_pk_bf16(v0[2], v0[3]); w.z = cvt_pk_bf16(v1[0], v1[1]); w.w = cvt_pk_bf16(v1[2], v1[3]); return w; }
; __device__ __forceinline__ float bf_lo(unsigned w) { return __uint_as_float(w << 16); }
; __device__ __forceinline__ float bf_hi(unsigned w) { return __uint_as_float(w & 0xffff0000u); }
;     __device__ __forceinline__ void operator()(const f32x4 (&acc)[2][2][4][2], const Unit& u, int wr, int wc, int fr, int fq) const {
;         u32x4 xo[2][4][2];
;         _Pragma("unroll") for (int ai = 0; ai < 2; ++ai) _Pragma("unroll") for (int m = 0; m < 4; ++m) _Pragma("unroll") for (int bj = 0; bj < 2; ++bj)
;             xo[ai][m][bj] = *(const u32x4*)(X + (size_t)EPI_ROW(ai, m) * 1024 + u.pn * BM + EPI_CT(bj));
;         _Pragma("unroll") for (int ai = 0; ai < 2; ++ai) _Pragma("unroll") for (int m = 0; m < 4; ++m) _Pragma("unroll") for (int bj = 0; bj < 2; ++bj) {
;             f32x4 v0 = acc[ai][bj][m][0], v1 = acc[ai][bj][m][1]; const u32x4 o = xo[ai][m][bj];
;             v0[0] += bf_lo(o.x); v0[1] += bf_hi(o.x); v0[2] += bf_lo(o.y); v0[3] += bf_hi(o.y); v1[0] += bf_lo(o.z); v1[1] += bf_hi(o.z); v1[2] += bf_lo(o.w); v1[3] += bf_hi(o.w);
;             *(u32x4*)(X + (size_t)EPI_ROW(ai, m) * 1024 + u.pn * BM + EPI_CT(bj)) = pack8(v0, v1); }
;     }
.LBB0_700:
	s_lshl_b32 s16, s37, 8
	s_ashr_i32 s17, s16, 31
	v_lshl_add_u32 v134, s38, 8, v230
	s_lshl_b64 s[20:21], s[16:17], 1
	s_add_u32 s16, s6, s20
	v_ashrrev_i32_e32 v135, 31, v134
	s_addc_u32 s17, s7, s21
	v_lshlrev_b64 v[228:229], 11, v[134:135]
	v_lshl_add_u64 v[130:131], s[16:17], 0, v[228:229]
	v_lshl_add_u64 v[130:131], v[130:131], 0, v[0:1]
	global_load_dwordx4 v[190:193], v[130:131], off
	global_load_dwordx4 v[186:189], v[130:131], off offset:256
	v_or_b32_e32 v130, 16, v134
	v_ashrrev_i32_e32 v131, 31, v130
	v_lshlrev_b64 v[226:227], 11, v[130:131]
	v_lshl_add_u64 v[130:131], s[16:17], 0, v[226:227]
	v_lshl_add_u64 v[130:131], v[130:131], 0, v[0:1]
	global_load_dwordx4 v[182:185], v[130:131], off
	global_load_dwordx4 v[178:181], v[130:131], off offset:256
	v_or_b32_e32 v130, 32, v134
	v_ashrrev_i32_e32 v131, 31, v130
	v_lshlrev_b64 v[224:225], 11, v[130:131]
	v_lshl_add_u64 v[130:131], s[16:17], 0, v[224:225]
	v_lshl_add_u64 v[130:131], v[130:131], 0, v[0:1]
	global_load_dwordx4 v[174:177], v[130:131], off
	global_load_dwordx4 v[166:169], v[130:131], off offset:256
	v_or_b32_e32 v130, 48, v134
	v_ashrrev_i32_e32 v131, 31, v130
	v_lshlrev_b64 v[222:223], 11, v[130:131]
	v_lshl_add_u64 v[130:131], s[16:17], 0, v[222:223]
	v_lshl_add_u64 v[130:131], v[130:131], 0, v[0:1]
	global_load_dwordx4 v[170:173], v[130:131], off
	global_load_dwordx4 v[162:165], v[130:131], off offset:256
	v_add_u32_e32 v130, 0x80, v134
	v_ashrrev_i32_e32 v131, 31, v130
	v_lshlrev_b64 v[220:221], 11, v[130:131]
	v_lshl_add_u64 v[130:131], s[16:17], 0, v[220:221]
	v_lshl_add_u64 v[130:131], v[130:131], 0, v[0:1]
	global_load_dwordx4 v[158:161], v[130:131], off
	global_load_dwordx4 v[154:157], v[130:131], off offset:256
	v_add_u32_e32 v130, 0x90, v134
	v_ashrrev_i32_e32 v131, 31, v130
	v_lshlrev_b64 v[210:211], 11, v[130:131]
	v_lshl_add_u64 v[130:131], s[16:17], 0, v[210:211]
	v_lshl_add_u64 v[130:131], v[130:131], 0, v[0:1]
	global_load_dwordx4 v[150:153], v[130:131], off
	global_load_dwordx4 v[142:145], v[130:131], off offset:256
	v_add_u32_e32 v130, 0xa0, v134
	v_ashrrev_i32_e32 v131, 31, v130
	v_lshlrev_b64 v[206:207], 11, v[130:131]
	v_lshl_add_u64 v[130:131], s[16:17], 0, v[206:207]
	v_lshl_add_u64 v[130:131], v[130:131], 0, v[0:1]
	global_load_dwordx4 v[138:141], v[130:131], off
	s_nop 0
	global_load_dwordx4 v[130:133], v[130:131], off offset:256
	v_add_u32_e32 v134, 0xb0, v134
	v_ashrrev_i32_e32 v135, 31, v134
	v_lshlrev_b64 v[208:209], 11, v[134:135]
	v_lshl_add_u64 v[134:135], s[16:17], 0, v[208:209]
	v_lshl_add_u64 v[134:135], v[134:135], 0, v[0:1]
	global_load_dwordx4 v[146:149], v[134:135], off
	s_nop 0
	global_load_dwordx4 v[134:137], v[134:135], off offset:256
	s_mov_b64 s[16:17], -1
	s_andn2_b64 vcc, exec, s[4:5]
	s_waitcnt vmcnt(15)
	v_lshlrev_b32_e32 v212, 16, v190
	v_and_b32_e32 v213, 0xffff0000, v190
	v_lshlrev_b32_e32 v190, 16, v191
	v_and_b32_e32 v191, 0xffff0000, v191
	v_pk_add_f32 v[128:129], v[128:129], v[190:191]
	v_lshlrev_b32_e32 v190, 16, v192
	v_and_b32_e32 v191, 0xffff0000, v192
	v_pk_add_f32 v[126:127], v[126:127], v[212:213]
	v_pk_add_f32 v[190:191], v[122:123], v[190:191]
	v_lshlrev_b32_e32 v122, 16, v193
	v_and_b32_e32 v123, 0xffff0000, v193
	v_pk_add_f32 v[192:193], v[124:125], v[122:123]
	v_cvt_pk_bf16_f32 v122, v126, v127
	v_lshl_add_u64 v[126:127], s[6:7], 0, v[228:229]
	v_lshl_add_u64 v[126:127], v[126:127], 0, s[20:21]
	v_cvt_pk_bf16_f32 v123, v128, v129
	v_cvt_pk_bf16_f32 v124, v190, v191
	v_cvt_pk_bf16_f32 v125, v192, v193
	v_lshl_add_u64 v[126:127], v[126:127], 0, v[0:1]
	global_store_dwordx4 v[126:127], v[122:125], off
	s_waitcnt vmcnt(15)
	s_nop 1
	v_lshlrev_b32_e32 v122, 16, v186
	v_and_b32_e32 v123, 0xffff0000, v186
	v_pk_add_f32 v[118:119], v[118:119], v[122:123]
	v_lshlrev_b32_e32 v122, 16, v187
	v_and_b32_e32 v123, 0xffff0000, v187
	v_pk_add_f32 v[120:121], v[120:121], v[122:123]
	v_lshlrev_b32_e32 v122, 16, v188
	v_and_b32_e32 v123, 0xffff0000, v188
	v_pk_add_f32 v[122:123], v[110:111], v[122:123]
	v_lshlrev_b32_e32 v110, 16, v189
	v_and_b32_e32 v111, 0xffff0000, v189
	v_pk_add_f32 v[124:125], v[112:113], v[110:111]
	v_cvt_pk_bf16_f32 v110, v118, v119
	v_cvt_pk_bf16_f32 v111, v120, v121
	v_cvt_pk_bf16_f32 v112, v122, v123
	v_cvt_pk_bf16_f32 v113, v124, v125
	global_store_dwordx4 v[126:127], v[110:113], off offset:256
	s_waitcnt vmcnt(15)
	s_nop 1
	v_lshlrev_b32_e32 v110, 16, v182
	v_and_b32_e32 v111, 0xffff0000, v182
	v_pk_add_f32 v[110:111], v[114:115], v[110:111]
	v_lshlrev_b32_e32 v114, 16, v184
	v_and_b32_e32 v115, 0xffff0000, v184
	v_lshlrev_b32_e32 v112, 16, v183
	v_and_b32_e32 v113, 0xffff0000, v183
	v_pk_add_f32 v[114:115], v[106:107], v[114:115]
	v_lshlrev_b32_e32 v106, 16, v185
	v_and_b32_e32 v107, 0xffff0000, v185
	v_pk_add_f32 v[112:113], v[116:117], v[112:113]
	v_pk_add_f32 v[116:117], v[108:109], v[106:107]
	v_cvt_pk_bf16_f32 v106, v110, v111
	v_lshl_add_u64 v[110:111], s[6:7], 0, v[226:227]
	v_lshl_add_u64 v[110:111], v[110:111], 0, s[20:21]
	v_cvt_pk_bf16_f32 v107, v112, v113
	v_cvt_pk_bf16_f32 v108, v114, v115
	v_cvt_pk_bf16_f32 v109, v116, v117
	v_lshl_add_u64 v[110:111], v[110:111], 0, v[0:1]
	global_store_dwordx4 v[110:111], v[106:109], off
	s_waitcnt vmcnt(15)
	s_nop 1
	v_lshlrev_b32_e32 v106, 16, v178
	v_and_b32_e32 v107, 0xffff0000, v178
	v_pk_add_f32 v[102:103], v[102:103], v[106:107]
	v_lshlrev_b32_e32 v106, 16, v179
	v_and_b32_e32 v107, 0xffff0000, v179
	v_pk_add_f32 v[104:105], v[104:105], v[106:107]
	v_lshlrev_b32_e32 v106, 16, v180
	v_and_b32_e32 v107, 0xffff0000, v180
	v_pk_add_f32 v[106:107], v[94:95], v[106:107]
	v_lshlrev_b32_e32 v94, 16, v181
	v_and_b32_e32 v95, 0xffff0000, v181
	v_pk_add_f32 v[108:109], v[96:97], v[94:95]
	v_cvt_pk_bf16_f32 v94, v102, v103
	v_cvt_pk_bf16_f32 v95, v104, v105
	v_cvt_pk_bf16_f32 v96, v106, v107
	v_cvt_pk_bf16_f32 v97, v108, v109
	global_store_dwordx4 v[110:111], v[94:97], off offset:256
	s_waitcnt vmcnt(15)
; __device__ __forceinline__ u32x4 pack8(const f32x4 v0, const f32x4 v1) { u32x4 w; w.x = cvt_pk_bf16(v0[0], v0[1]); w.y = cvt_pk_bf16(v0[2], v0[3]); w.z = cvt_pk_bf16(v1[0], v1[1]); w.w = cvt_pk_bf16(v1[2], v1[3]); return w; }
; __device__ __forceinline__ float bf_lo(unsigned w) { return __uint_as_float(w << 16); }
; __device__ __forceinline__ float bf_hi(unsigned w) { return __uint_as_float(w & 0xffff0000u); }
;     __device__ __forceinline__ void operator()(const f32x4 (&acc)[2][2][4][2], const Unit& u, int wr, int wc, int fr, int fq) const {
;     ...
;         _Pragma("unroll") for (int ai = 0; ai < 2; ++ai) _Pragma("unroll") for (int m = 0; m < 4; ++m) _Pragma("unroll") for (int bj = 0; bj < 2; ++bj) {
;             f32x4 v0 = acc[ai][bj][m][0], v1 = acc[ai][bj][m][1]; const u32x4 o = xo[ai][m][bj];
;             v0[0] += bf_lo(o.x); v0[1] += bf_hi(o.x); v0[2] += bf_lo(o.y); v0[3] += bf_hi(o.y); v1[0] += bf_lo(o.z); v1[1] += bf_hi(o.z); v1[2] += bf_lo(o.w); v1[3] += bf_hi(o.w);
;             *(u32x4*)(X + (size_t)EPI_ROW(ai, m) * 1024 + u.pn * BM + EPI_CT(bj)) = pack8(v0, v1); }
	s_nop 1
	v_lshlrev_b32_e32 v94, 16, v174
	v_and_b32_e32 v95, 0xffff0000, v174
	v_pk_add_f32 v[94:95], v[98:99], v[94:95]
	v_lshlrev_b32_e32 v98, 16, v176
	v_and_b32_e32 v99, 0xffff0000, v176
	v_lshlrev_b32_e32 v96, 16, v175
	v_and_b32_e32 v97, 0xffff0000, v175
	v_pk_add_f32 v[98:99], v[90:91], v[98:99]
	v_lshlrev_b32_e32 v90, 16, v177
	v_and_b32_e32 v91, 0xffff0000, v177
	v_pk_add_f32 v[96:97], v[100:101], v[96:97]
	v_pk_add_f32 v[100:101], v[92:93], v[90:91]
	v_cvt_pk_bf16_f32 v90, v94, v95
	v_lshl_add_u64 v[94:95], s[6:7], 0, v[224:225]
	v_lshl_add_u64 v[94:95], v[94:95], 0, s[20:21]
	v_cvt_pk_bf16_f32 v91, v96, v97
	v_cvt_pk_bf16_f32 v92, v98, v99
	v_cvt_pk_bf16_f32 v93, v100, v101
	v_lshl_add_u64 v[94:95], v[94:95], 0, v[0:1]
	global_store_dwordx4 v[94:95], v[90:93], off
	s_waitcnt vmcnt(15)
	s_nop 1
	v_lshlrev_b32_e32 v90, 16, v166
	v_and_b32_e32 v91, 0xffff0000, v166
	v_pk_add_f32 v[86:87], v[86:87], v[90:91]
	v_lshlrev_b32_e32 v90, 16, v167
	v_and_b32_e32 v91, 0xffff0000, v167
	v_pk_add_f32 v[88:89], v[88:89], v[90:91]
	v_lshlrev_b32_e32 v90, 16, v168
	v_and_b32_e32 v91, 0xffff0000, v168
	v_pk_add_f32 v[90:91], v[78:79], v[90:91]
	v_lshlrev_b32_e32 v78, 16, v169
	v_and_b32_e32 v79, 0xffff0000, v169
	v_pk_add_f32 v[92:93], v[80:81], v[78:79]
	v_cvt_pk_bf16_f32 v78, v86, v87
	v_cvt_pk_bf16_f32 v79, v88, v89
	v_cvt_pk_bf16_f32 v80, v90, v91
	v_cvt_pk_bf16_f32 v81, v92, v93
	global_store_dwordx4 v[94:95], v[78:81], off offset:256
	s_waitcnt vmcnt(15)
	s_nop 1
	v_lshlrev_b32_e32 v78, 16, v170
	v_and_b32_e32 v79, 0xffff0000, v170
	v_pk_add_f32 v[78:79], v[82:83], v[78:79]
	v_lshlrev_b32_e32 v82, 16, v172
	v_and_b32_e32 v83, 0xffff0000, v172
	v_lshlrev_b32_e32 v80, 16, v171
	v_and_b32_e32 v81, 0xffff0000, v171
	v_pk_add_f32 v[82:83], v[74:75], v[82:83]
	v_lshlrev_b32_e32 v74, 16, v173
	v_and_b32_e32 v75, 0xffff0000, v173
	v_pk_add_f32 v[80:81], v[84:85], v[80:81]
	v_pk_add_f32 v[84:85], v[76:77], v[74:75]
	v_cvt_pk_bf16_f32 v74, v78, v79
	v_lshl_add_u64 v[78:79], s[6:7], 0, v[222:223]
	v_lshl_add_u64 v[78:79], v[78:79], 0, s[20:21]
	v_cvt_pk_bf16_f32 v75, v80, v81
	v_cvt_pk_bf16_f32 v76, v82, v83
	v_cvt_pk_bf16_f32 v77, v84, v85
	v_lshl_add_u64 v[78:79], v[78:79], 0, v[0:1]
	global_store_dwordx4 v[78:79], v[74:77], off
	s_waitcnt vmcnt(15)
	s_nop 1
	v_lshlrev_b32_e32 v74, 16, v162
	v_and_b32_e32 v75, 0xffff0000, v162
	v_pk_add_f32 v[70:71], v[70:71], v[74:75]
	v_lshlrev_b32_e32 v74, 16, v163
	v_and_b32_e32 v75, 0xffff0000, v163
	v_pk_add_f32 v[72:73], v[72:73], v[74:75]
	v_lshlrev_b32_e32 v74, 16, v164
	v_and_b32_e32 v75, 0xffff0000, v164
	v_pk_add_f32 v[74:75], v[66:67], v[74:75]
	v_lshlrev_b32_e32 v66, 16, v165
	v_and_b32_e32 v67, 0xffff0000, v165
	v_pk_add_f32 v[76:77], v[68:69], v[66:67]
	v_cvt_pk_bf16_f32 v66, v70, v71
	v_cvt_pk_bf16_f32 v67, v72, v73
	v_cvt_pk_bf16_f32 v68, v74, v75
	v_cvt_pk_bf16_f32 v69, v76, v77
	global_store_dwordx4 v[78:79], v[66:69], off offset:256
	s_waitcnt vmcnt(15)
	s_nop 1
	v_lshlrev_b32_e32 v66, 16, v158
	v_and_b32_e32 v67, 0xffff0000, v158
	v_pk_add_f32 v[62:63], v[62:63], v[66:67]
	v_lshlrev_b32_e32 v66, 16, v159
	v_and_b32_e32 v67, 0xffff0000, v159
	v_pk_add_f32 v[64:65], v[64:65], v[66:67]
	v_lshlrev_b32_e32 v66, 16, v160
	v_and_b32_e32 v67, 0xffff0000, v160
	v_pk_add_f32 v[66:67], v[58:59], v[66:67]
	v_lshlrev_b32_e32 v58, 16, v161
	v_and_b32_e32 v59, 0xffff0000, v161
	v_pk_add_f32 v[68:69], v[60:61], v[58:59]
	v_cvt_pk_bf16_f32 v58, v62, v63
	v_lshl_add_u64 v[62:63], s[6:7], 0, v[220:221]
	v_lshl_add_u64 v[62:63], v[62:63], 0, s[20:21]
	v_cvt_pk_bf16_f32 v59, v64, v65
	v_cvt_pk_bf16_f32 v60, v66, v67
	v_cvt_pk_bf16_f32 v61, v68, v69
	v_lshl_add_u64 v[62:63], v[62:63], 0, v[0:1]
	global_store_dwordx4 v[62:63], v[58:61], off
	s_waitcnt vmcnt(15)
	s_nop 1
	v_lshlrev_b32_e32 v58, 16, v154
	v_and_b32_e32 v59, 0xffff0000, v154
	v_pk_add_f32 v[54:55], v[54:55], v[58:59]
	v_lshlrev_b32_e32 v58, 16, v155
	v_and_b32_e32 v59, 0xffff0000, v155
	v_pk_add_f32 v[56:57], v[56:57], v[58:59]
	v_lshlrev_b32_e32 v58, 16, v156
	v_and_b32_e32 v59, 0xffff0000, v156
	v_pk_add_f32 v[58:59], v[46:47], v[58:59]
	v_lshlrev_b32_e32 v46, 16, v157
	v_and_b32_e32 v47, 0xffff0000, v157
	v_pk_add_f32 v[60:61], v[48:49], v[46:47]
	v_cvt_pk_bf16_f32 v46, v54, v55
	v_cvt_pk_bf16_f32 v47, v56, v57
	v_cvt_pk_bf16_f32 v48, v58, v59
	v_cvt_pk_bf16_f32 v49, v60, v61
	global_store_dwordx4 v[62:63], v[46:49], off offset:256
	s_waitcnt vmcnt(15)
; __device__ __forceinline__ u32x4 pack8(const f32x4 v0, const f32x4 v1) { u32x4 w; w.x = cvt_pk_bf16(v0[0], v0[1]); w.y = cvt_pk_bf16(v0[2], v0[3]); w.z = cvt_pk_bf16(v1[0], v1[1]); w.w = cvt_pk_bf16(v1[2], v1[3]); return w; }
; __device__ __forceinline__ float bf_lo(unsigned w) { return __uint_as_float(w << 16); }
; __device__ __forceinline__ float bf_hi(unsigned w) { return __uint_as_float(w & 0xffff0000u); }
;     __device__ __forceinline__ void operator()(const f32x4 (&acc)[2][2][4][2], const Unit& u, int wr, int wc, int fr, int fq) const {
;     ...
;         _Pragma("unroll") for (int ai = 0; ai < 2; ++ai) _Pragma("unroll") for (int m = 0; m < 4; ++m) _Pragma("unroll") for (int bj = 0; bj < 2; ++bj) {
;             f32x4 v0 = acc[ai][bj][m][0], v1 = acc[ai][bj][m][1]; const u32x4 o = xo[ai][m][bj];
;             v0[0] += bf_lo(o.x); v0[1] += bf_hi(o.x); v0[2] += bf_lo(o.y); v0[3] += bf_hi(o.y); v1[0] += bf_lo(o.z); v1[1] += bf_hi(o.z); v1[2] += bf_lo(o.w); v1[3] += bf_hi(o.w);
;             *(u32x4*)(X + (size_t)EPI_ROW(ai, m) * 1024 + u.pn * BM + EPI_CT(bj)) = pack8(v0, v1); }
; template <class Epi, class Sched, bool ALIGN_EPI = false, bool SP2 = false>
; __device__ __forceinline__ void gemm_phase(PG8_LAS unsigned char* lds, const Gemm g, const Sched& S, const Epi& E) {
;     ...
;         if constexpr (!Epi::AFTER_DRAIN) { E(acc, cur, wr, wc, fr, fq); S.done(cur); }
;         if (!has_next) break;
	s_nop 1
	v_lshlrev_b32_e32 v46, 16, v150
	v_and_b32_e32 v47, 0xffff0000, v150
	v_pk_add_f32 v[46:47], v[50:51], v[46:47]
	v_lshlrev_b32_e32 v50, 16, v152
	v_and_b32_e32 v51, 0xffff0000, v152
	v_lshlrev_b32_e32 v48, 16, v151
	v_and_b32_e32 v49, 0xffff0000, v151
	v_pk_add_f32 v[50:51], v[42:43], v[50:51]
	v_lshlrev_b32_e32 v42, 16, v153
	v_and_b32_e32 v43, 0xffff0000, v153
	v_pk_add_f32 v[48:49], v[52:53], v[48:49]
	v_pk_add_f32 v[52:53], v[44:45], v[42:43]
	v_cvt_pk_bf16_f32 v42, v46, v47
	v_lshl_add_u64 v[46:47], s[6:7], 0, v[210:211]
	v_lshl_add_u64 v[46:47], v[46:47], 0, s[20:21]
	v_cvt_pk_bf16_f32 v43, v48, v49
	v_cvt_pk_bf16_f32 v44, v50, v51
	v_cvt_pk_bf16_f32 v45, v52, v53
	v_lshl_add_u64 v[46:47], v[46:47], 0, v[0:1]
	global_store_dwordx4 v[46:47], v[42:45], off
	s_waitcnt vmcnt(15)
	s_nop 1
	v_lshlrev_b32_e32 v42, 16, v142
	v_and_b32_e32 v43, 0xffff0000, v142
	v_pk_add_f32 v[38:39], v[38:39], v[42:43]
	v_lshlrev_b32_e32 v42, 16, v143
	v_and_b32_e32 v43, 0xffff0000, v143
	v_pk_add_f32 v[40:41], v[40:41], v[42:43]
	v_lshlrev_b32_e32 v42, 16, v144
	v_and_b32_e32 v43, 0xffff0000, v144
	v_pk_add_f32 v[42:43], v[30:31], v[42:43]
	v_lshlrev_b32_e32 v30, 16, v145
	v_and_b32_e32 v31, 0xffff0000, v145
	v_pk_add_f32 v[44:45], v[32:33], v[30:31]
	v_cvt_pk_bf16_f32 v30, v38, v39
	v_cvt_pk_bf16_f32 v31, v40, v41
	v_cvt_pk_bf16_f32 v32, v42, v43
	v_cvt_pk_bf16_f32 v33, v44, v45
	global_store_dwordx4 v[46:47], v[30:33], off offset:256
	s_waitcnt vmcnt(15)
	s_nop 1
	v_lshlrev_b32_e32 v30, 16, v138
	v_and_b32_e32 v31, 0xffff0000, v138
	v_pk_add_f32 v[30:31], v[34:35], v[30:31]
	v_lshlrev_b32_e32 v34, 16, v140
	v_and_b32_e32 v35, 0xffff0000, v140
	v_lshlrev_b32_e32 v32, 16, v139
	v_and_b32_e32 v33, 0xffff0000, v139
	v_pk_add_f32 v[34:35], v[26:27], v[34:35]
	v_lshlrev_b32_e32 v26, 16, v141
	v_and_b32_e32 v27, 0xffff0000, v141
	v_pk_add_f32 v[32:33], v[36:37], v[32:33]
	v_pk_add_f32 v[36:37], v[28:29], v[26:27]
	v_cvt_pk_bf16_f32 v26, v30, v31
	v_lshl_add_u64 v[30:31], s[6:7], 0, v[206:207]
	v_lshl_add_u64 v[30:31], v[30:31], 0, s[20:21]
	v_cvt_pk_bf16_f32 v27, v32, v33
	v_cvt_pk_bf16_f32 v28, v34, v35
	v_cvt_pk_bf16_f32 v29, v36, v37
	v_lshl_add_u64 v[30:31], v[30:31], 0, v[0:1]
	global_store_dwordx4 v[30:31], v[26:29], off
	s_waitcnt vmcnt(15)
	s_nop 1
	v_lshlrev_b32_e32 v26, 16, v130
	v_and_b32_e32 v27, 0xffff0000, v130
	v_pk_add_f32 v[22:23], v[22:23], v[26:27]
	v_lshlrev_b32_e32 v26, 16, v131
	v_and_b32_e32 v27, 0xffff0000, v131
	v_pk_add_f32 v[24:25], v[24:25], v[26:27]
	v_lshlrev_b32_e32 v26, 16, v132
	v_and_b32_e32 v27, 0xffff0000, v132
	v_pk_add_f32 v[26:27], v[14:15], v[26:27]
	v_lshlrev_b32_e32 v14, 16, v133
	v_and_b32_e32 v15, 0xffff0000, v133
	v_pk_add_f32 v[28:29], v[16:17], v[14:15]
	v_cvt_pk_bf16_f32 v14, v22, v23
	v_cvt_pk_bf16_f32 v15, v24, v25
	v_cvt_pk_bf16_f32 v16, v26, v27
	v_cvt_pk_bf16_f32 v17, v28, v29
	global_store_dwordx4 v[30:31], v[14:17], off offset:256
	s_waitcnt vmcnt(15)
	s_nop 1
	v_lshlrev_b32_e32 v14, 16, v146
	v_and_b32_e32 v15, 0xffff0000, v146
	v_pk_add_f32 v[14:15], v[18:19], v[14:15]
	v_lshlrev_b32_e32 v18, 16, v148
	v_and_b32_e32 v19, 0xffff0000, v148
	v_lshlrev_b32_e32 v16, 16, v147
	v_and_b32_e32 v17, 0xffff0000, v147
	v_pk_add_f32 v[18:19], v[10:11], v[18:19]
	v_lshlrev_b32_e32 v10, 16, v149
	v_and_b32_e32 v11, 0xffff0000, v149
	v_pk_add_f32 v[16:17], v[20:21], v[16:17]
	v_pk_add_f32 v[20:21], v[12:13], v[10:11]
	v_cvt_pk_bf16_f32 v10, v14, v15
	v_lshl_add_u64 v[14:15], s[6:7], 0, v[208:209]
	v_lshl_add_u64 v[14:15], v[14:15], 0, s[20:21]
	v_cvt_pk_bf16_f32 v11, v16, v17
	v_cvt_pk_bf16_f32 v12, v18, v19
	v_cvt_pk_bf16_f32 v13, v20, v21
	v_lshl_add_u64 v[14:15], v[14:15], 0, v[0:1]
	global_store_dwordx4 v[14:15], v[10:13], off
	s_waitcnt vmcnt(15)
	s_nop 1
	v_lshlrev_b32_e32 v10, 16, v134
	v_and_b32_e32 v11, 0xffff0000, v134
	v_pk_add_f32 v[6:7], v[6:7], v[10:11]
	v_lshlrev_b32_e32 v10, 16, v135
	v_and_b32_e32 v11, 0xffff0000, v135
	v_pk_add_f32 v[8:9], v[8:9], v[10:11]
	v_lshlrev_b32_e32 v10, 16, v136
	v_and_b32_e32 v11, 0xffff0000, v136
	v_pk_add_f32 v[10:11], v[2:3], v[10:11]
	v_lshlrev_b32_e32 v2, 16, v137
	v_and_b32_e32 v3, 0xffff0000, v137
	v_pk_add_f32 v[12:13], v[4:5], v[2:3]
	v_cvt_pk_bf16_f32 v2, v6, v7
	v_cvt_pk_bf16_f32 v3, v8, v9
	v_cvt_pk_bf16_f32 v4, v10, v11
	v_cvt_pk_bf16_f32 v5, v12, v13
	global_store_dwordx4 v[14:15], v[2:5], off offset:256
	s_cbranch_vccnz .LBB0_689
	s_andn2_b64 vcc, exec, s[0:1]
	s_cbranch_vccnz .LBB0_688
	s_branch .LBB0_688
